# A1 A-stream: softmax of the second S half deferred to the next tile top (overlapping the K fragment prefill latency), leaving only 8 VALU-carrying PV gaps
# baseline (speedup 1.0000x reference)
; template <int NHQ, int NHKV>
; DI void attn_phase_l1(const u16* __restrict__ Q, const u16* __restrict__ K, const u16* __restrict__ Vt, u16* __restrict__ O, const float* __restrict__ qg, char* smem, const int wv) {
;     ...
;   for (int item = (G_ % 8 == 0) ? (b_ % 8) * (G_ / 8) + b_ / 8 : b_; item < NF; item += G_) {
;     const int hq = (item >> 4) % NHQ, sq = item / (16 * NHQ), q0 = NMETA + 256 * (item & 15);
;     const u16* Kb = K + (size_t)(sq * L) * LDK + (hq / (NHQ / NHKV)) * DQK;
;     const u16* Vb = Vt + (size_t)((sq * NHKV + hq / (NHQ / NHKV)) * 128) * LP;
;     const int pq = q0 + wave * 32 + r32;
;     {
;       const u16* qrow = Q + (size_t)(sq * L + pq) * 1280 + hq * DQK + hh * 8;
;       int hho = hh; asm volatile("" : "+v"(hho));
;       float ssq = 0.f;
; #pragma unroll
;       for (int i = 0; i < NS; ++i) {
;         qf[i] = *(const bf16x8*)(qrow + 16 * i);
;         float t8[8]; unpack8(__builtin_bit_cast(u32x4, qf[i]), t8);
; #pragma unroll
;         for (int e = 0; e < 8; ++e) ssq += t8[e] * t8[e];
;       }
;       ssq = xhalf_sum(ssq);
;       const float rn = rsqrtf(ssq * (1.f / DQK) + EPS) * (0.08838834764831845f * 1.4426950408889634f);
;     ...
;       const float prow = (float)((pq - NMETA) >> 6), pcol = (float)((pq - NMETA) & 63);
;       A_QROPE(0, 2, 0, prow); A_QROPE(1, 3, 1, prow);
;       A_QROPE(4, 6, 0, pcol); A_QROPE(5, 7, 1, pcol);
.LBB0_1216:
	s_ashr_i32 s18, s28, 4
	s_lshr_b32 s19, s18, 29
	s_add_i32 s19, s18, s19
	s_and_b32 s19, s19, -8
	s_sub_i32 s24, s18, s19
	s_ashr_i32 s18, s28, 31
	s_lshr_b32 s18, s18, 25
	s_add_i32 s18, s28, s18
	s_ashr_i32 s41, s18, 7
	s_lshl_b32 s18, s28, 8
	s_and_b32 s25, s18, 0xf00
	s_mul_i32 s18, s41, 0x1010
	s_ashr_i32 s19, s18, 31
	s_lshl_b64 s[20:21], s[18:19], 9
	s_bfe_i32 s19, s24, 0x80000
	s_bfe_u32 s19, s19, 0x2000d
	s_add_i32 s19, s24, s19
	s_sext_i32_i8 s19, s19
	s_lshl_b32 s19, s19, 5
	v_add_u32_e32 v2, s25, v202
	s_and_b32 s22, s19, 0xffffff80
	s_lshl_b32 s19, s41, 8
	v_add_u32_e32 v0, s18, v2
	s_add_i32 s42, s22, s19
	v_mad_i64_i32 v[0:1], s[18:19], v0, s35, v[168:169]
	s_lshl_b32 s18, s24, 7
	s_ashr_i32 s19, s18, 31
	v_lshl_add_u64 v[0:1], s[18:19], 1, v[0:1]
	v_mov_b32_e32 v3, v200
	v_lshl_add_u64 v[0:1], v[0:1], 0, v[170:171]
	global_load_dwordx4 v[68:71], v[0:1], off
	global_load_dwordx4 v[76:79], v[0:1], off offset:32
	global_load_dwordx4 v[64:67], v[0:1], off offset:64
	global_load_dwordx4 v[72:75], v[0:1], off offset:96
	global_load_dwordx4 v[84:87], v[0:1], off offset:128
	global_load_dwordx4 v[92:95], v[0:1], off offset:160
	global_load_dwordx4 v[80:83], v[0:1], off offset:192
	global_load_dwordx4 v[88:91], v[0:1], off offset:224
	v_lshlrev_b32_e32 v17, 3, v3
	v_cvt_f32_i32_e32 v1, v17
	v_add_u32_e32 v173, -16, v2
	v_ashrrev_i32_e32 v0, 6, v173
	v_cvt_f32_i32_e32 v18, v0
	v_mul_f32_e32 v0, 0xbed49a78, v1
	v_cmp_gt_f32_e32 vcc, s36, v0
	global_load_dwordx4 v[28:31], v[166:167], off
	global_load_dwordx4 v[24:27], v[166:167], off offset:16
	v_cndmask_b32_e32 v0, 0, v208, vcc
	v_fmac_f32_e32 v0, 0xbed49a78, v1
	v_exp_f32_e32 v0, v0
	v_cndmask_b32_e32 v1, 0, v209, vcc
	global_load_dwordx4 v[36:39], v[166:167], off offset:128
	global_load_dwordx4 v[32:35], v[166:167], off offset:144
	v_and_b32_e32 v16, 63, v173
	v_ldexp_f32 v19, v0, v1
	v_or_b32_e32 v1, 1, v17
	v_cvt_f32_i32_e32 v1, v1
	v_mul_f32_e32 v0, v19, v18
	v_mul_f32_e32 v2, 0.15915494, v0
	v_floor_f32_e32 v2, v2
	v_fma_f32 v0, v0, 0.15915494, -v2
	v_mul_f32_e32 v2, 0xbed49a78, v1
	v_cmp_gt_f32_e32 vcc, s36, v2
	v_sin_f32_e32 v96, v0
	v_cos_f32_e32 v98, v0
	v_cndmask_b32_e32 v2, 0, v208, vcc
	v_fmac_f32_e32 v2, 0xbed49a78, v1
	v_exp_f32_e32 v1, v2
	v_cndmask_b32_e32 v0, 0, v209, vcc
	v_cvt_f32_ubyte0_e32 v155, v16
	v_mul_f32_e32 v16, v19, v155
	v_ldexp_f32 v20, v1, v0
	v_or_b32_e32 v1, 2, v17
	v_cvt_f32_i32_e32 v1, v1
	v_mul_f32_e32 v0, v20, v18
	v_mul_f32_e32 v2, 0.15915494, v0
	v_floor_f32_e32 v2, v2
	v_fma_f32 v0, v0, 0.15915494, -v2
	v_mul_f32_e32 v2, 0xbed49a78, v1
	v_cmp_gt_f32_e32 vcc, s36, v2
	v_sin_f32_e32 v97, v0
	v_cos_f32_e32 v99, v0
	v_cndmask_b32_e32 v2, 0, v208, vcc
	v_fmac_f32_e32 v2, 0xbed49a78, v1
	v_exp_f32_e32 v1, v2
	v_cndmask_b32_e32 v0, 0, v209, vcc
	s_ashr_i32 s23, s22, 31
	s_add_u32 s24, s29, s20
	v_ldexp_f32 v21, v1, v0
	v_or_b32_e32 v1, 3, v17
	v_cvt_f32_i32_e32 v1, v1
	v_mul_f32_e32 v0, v21, v18
	v_mul_f32_e32 v2, 0.15915494, v0
	v_floor_f32_e32 v2, v2
	v_fma_f32 v0, v0, 0.15915494, -v2
	v_mul_f32_e32 v2, 0xbed49a78, v1
	v_cmp_gt_f32_e32 vcc, s36, v2
	v_sin_f32_e32 v100, v0
	v_cos_f32_e32 v102, v0
	v_cndmask_b32_e32 v2, 0, v208, vcc
	v_fmac_f32_e32 v2, 0xbed49a78, v1
	v_exp_f32_e32 v1, v2
	v_cndmask_b32_e32 v0, 0, v209, vcc
	s_addc_u32 s25, s30, s21
	s_lshl_b64 s[22:23], s[22:23], 1
	v_ldexp_f32 v22, v1, v0
	v_or_b32_e32 v1, 4, v17
	v_cvt_f32_i32_e32 v1, v1
	v_mul_f32_e32 v0, v22, v18
	v_mul_f32_e32 v2, 0.15915494, v0
	v_floor_f32_e32 v2, v2
	v_fma_f32 v0, v0, 0.15915494, -v2
	v_mul_f32_e32 v2, 0xbed49a78, v1
	v_cmp_gt_f32_e32 vcc, s36, v2
	v_sin_f32_e32 v101, v0
	v_cos_f32_e32 v103, v0
	v_cndmask_b32_e32 v2, 0, v208, vcc
	v_fmac_f32_e32 v2, 0xbed49a78, v1
	v_exp_f32_e32 v1, v2
	v_cndmask_b32_e32 v0, 0, v209, vcc
	s_waitcnt vmcnt(11)
	v_and_b32_e32 v223, 0xffff0000, v68
	v_lshlrev_b32_e32 v222, 16, v68
	v_ldexp_f32 v23, v1, v0
	v_or_b32_e32 v1, 5, v17
	v_cvt_f32_i32_e32 v1, v1
	v_mul_f32_e32 v0, v23, v18
	v_mul_f32_e32 v2, 0.15915494, v0
	v_floor_f32_e32 v2, v2
	v_fma_f32 v0, v0, 0.15915494, -v2
	v_mul_f32_e32 v2, 0xbed49a78, v1
	v_cmp_gt_f32_e32 vcc, s36, v2
	v_sin_f32_e32 v140, v0
	v_cos_f32_e32 v142, v0
	v_cndmask_b32_e32 v2, 0, v208, vcc
	v_fmac_f32_e32 v2, 0xbed49a78, v1
	v_exp_f32_e32 v1, v2
	v_cndmask_b32_e32 v0, 0, v209, vcc
	v_mul_f32_e32 v68, v223, v223
	s_waitcnt vmcnt(6)
	v_lshlrev_b32_e32 v158, 16, v95
	v_ldexp_f32 v40, v1, v0
	v_or_b32_e32 v1, 6, v17
	v_cvt_f32_i32_e32 v1, v1
	v_mul_f32_e32 v0, v40, v18
	v_mul_f32_e32 v2, 0.15915494, v0
	v_floor_f32_e32 v2, v2
	v_fma_f32 v0, v0, 0.15915494, -v2
	v_mul_f32_e32 v2, 0xbed49a78, v1
	v_cmp_gt_f32_e32 vcc, s36, v2
	v_sin_f32_e32 v141, v0
	v_cos_f32_e32 v143, v0
	v_cndmask_b32_e32 v2, 0, v208, vcc
	v_fmac_f32_e32 v2, 0xbed49a78, v1
	v_exp_f32_e32 v1, v2
	v_cndmask_b32_e32 v0, 0, v209, vcc
	v_and_b32_e32 v159, 0xffff0000, v95
	s_waitcnt vmcnt(4)
; template <int NHQ, int NHKV>
; DI void attn_phase_l1(const u16* __restrict__ Q, const u16* __restrict__ K, const u16* __restrict__ Vt, u16* __restrict__ O, const float* __restrict__ qg, char* smem, const int wv) {
;     ...
;     const int pq = q0 + wave * 32 + r32;
;     {
;       const u16* qrow = Q + (size_t)(sq * L + pq) * 1280 + hq * DQK + hh * 8;
;       int hho = hh; asm volatile("" : "+v"(hho));
;       float ssq = 0.f;
; #pragma unroll
;       for (int i = 0; i < NS; ++i) {
;         qf[i] = *(const bf16x8*)(qrow + 16 * i);
;         float t8[8]; unpack8(__builtin_bit_cast(u32x4, qf[i]), t8);
; #pragma unroll
;         for (int e = 0; e < 8; ++e) ssq += t8[e] * t8[e];
;       }
;       ssq = xhalf_sum(ssq);
;       const float rn = rsqrtf(ssq * (1.f / DQK) + EPS) * (0.08838834764831845f * 1.4426950408889634f);
;     ...
;       const float prow = (float)((pq - NMETA) >> 6), pcol = (float)((pq - NMETA) & 63);
;       A_QROPE(0, 2, 0, prow); A_QROPE(1, 3, 1, prow);
;       A_QROPE(4, 6, 0, pcol); A_QROPE(5, 7, 1, pcol);
	v_lshlrev_b32_e32 v156, 16, v91
	v_ldexp_f32 v41, v1, v0
	v_or_b32_e32 v1, 7, v17
	v_cvt_f32_i32_e32 v1, v1
	v_mul_f32_e32 v0, v41, v18
	v_mul_f32_e32 v2, 0.15915494, v0
	v_floor_f32_e32 v2, v2
	v_fma_f32 v0, v0, 0.15915494, -v2
	v_mul_f32_e32 v2, 0xbed49a78, v1
	v_cmp_gt_f32_e32 vcc, s36, v2
	v_sin_f32_e32 v180, v0
	v_cos_f32_e32 v182, v0
	v_cndmask_b32_e32 v2, 0, v208, vcc
	v_fmac_f32_e32 v2, 0xbed49a78, v1
	v_exp_f32_e32 v1, v2
	v_cndmask_b32_e32 v0, 0, v209, vcc
	v_and_b32_e32 v157, 0xffff0000, v91
	v_lshlrev_b32_e32 v174, 16, v94
	v_ldexp_f32 v42, v1, v0
	v_mul_f32_e32 v0, v42, v18
	v_mul_f32_e32 v1, 0.15915494, v0
	v_floor_f32_e32 v1, v1
	v_fma_f32 v0, v0, 0.15915494, -v1
	v_add_u32_e32 v1, 16, v17
	v_cvt_f32_i32_e32 v4, v1
	v_and_b32_e32 v175, 0xffff0000, v94
	v_lshlrev_b32_e32 v94, 16, v90
	v_and_b32_e32 v95, 0xffff0000, v90
	v_mul_f32_e32 v5, 0xbed49a78, v4
	v_cmp_gt_f32_e32 vcc, s36, v5
	v_lshlrev_b32_e32 v176, 16, v93
	v_and_b32_e32 v177, 0xffff0000, v93
	v_cndmask_b32_e32 v5, 0, v208, vcc
	v_fmac_f32_e32 v5, 0xbed49a78, v4
	v_exp_f32_e32 v43, v5
	v_cndmask_b32_e32 v44, 0, v209, vcc
	v_lshlrev_b32_e32 v90, 16, v89
	v_and_b32_e32 v91, 0xffff0000, v89
	v_ldexp_f32 v124, v43, v44
	v_add_u32_e32 v44, 17, v17
	v_cvt_f32_i32_e32 v44, v44
	v_mul_f32_e32 v43, v124, v18
	v_mul_f32_e32 v45, 0.15915494, v43
	v_floor_f32_e32 v45, v45
	v_fma_f32 v43, v43, 0.15915494, -v45
	v_mul_f32_e32 v45, 0xbed49a78, v44
	v_cmp_gt_f32_e32 vcc, s36, v45
	v_sin_f32_e32 v104, v43
	v_cos_f32_e32 v106, v43
	v_cndmask_b32_e32 v45, 0, v208, vcc
	v_fmac_f32_e32 v45, 0xbed49a78, v44
	v_exp_f32_e32 v44, v45
	v_cndmask_b32_e32 v43, 0, v209, vcc
	v_lshlrev_b32_e32 v178, 16, v92
	v_and_b32_e32 v179, 0xffff0000, v92
	v_ldexp_f32 v125, v44, v43
	v_add_u32_e32 v44, 18, v17
	v_cvt_f32_i32_e32 v44, v44
	v_mul_f32_e32 v43, v125, v18
	v_mul_f32_e32 v45, 0.15915494, v43
	v_floor_f32_e32 v45, v45
	v_fma_f32 v43, v43, 0.15915494, -v45
	v_mul_f32_e32 v45, 0xbed49a78, v44
	v_cmp_gt_f32_e32 vcc, s36, v45
	v_sin_f32_e32 v105, v43
	v_cos_f32_e32 v107, v43
	v_cndmask_b32_e32 v45, 0, v208, vcc
	v_fmac_f32_e32 v45, 0xbed49a78, v44
	v_exp_f32_e32 v44, v45
	v_cndmask_b32_e32 v43, 0, v209, vcc
	v_lshlrev_b32_e32 v92, 16, v88
	v_and_b32_e32 v93, 0xffff0000, v88
	v_ldexp_f32 v144, v44, v43
	v_add_u32_e32 v44, 19, v17
	v_cvt_f32_i32_e32 v44, v44
	v_mul_f32_e32 v43, v144, v18
	v_mul_f32_e32 v45, 0.15915494, v43
	v_floor_f32_e32 v45, v45
	v_fma_f32 v43, v43, 0.15915494, -v45
	v_mul_f32_e32 v45, 0xbed49a78, v44
	v_cmp_gt_f32_e32 vcc, s36, v45
	v_sin_f32_e32 v108, v43
	v_cos_f32_e32 v110, v43
	v_cndmask_b32_e32 v45, 0, v208, vcc
	v_fmac_f32_e32 v45, 0xbed49a78, v44
	v_exp_f32_e32 v44, v45
	v_cndmask_b32_e32 v43, 0, v209, vcc
	v_lshlrev_b32_e32 v184, 16, v87
	v_and_b32_e32 v185, 0xffff0000, v87
	v_ldexp_f32 v145, v44, v43
	v_add_u32_e32 v44, 20, v17
	v_cvt_f32_i32_e32 v44, v44
	v_mul_f32_e32 v43, v145, v18
	v_mul_f32_e32 v45, 0.15915494, v43
	v_floor_f32_e32 v45, v45
	v_fma_f32 v43, v43, 0.15915494, -v45
	v_mul_f32_e32 v45, 0xbed49a78, v44
	v_cmp_gt_f32_e32 vcc, s36, v45
	v_sin_f32_e32 v109, v43
	v_cos_f32_e32 v111, v43
	v_cndmask_b32_e32 v45, 0, v208, vcc
	v_fmac_f32_e32 v45, 0xbed49a78, v44
	v_exp_f32_e32 v44, v45
	v_cndmask_b32_e32 v43, 0, v209, vcc
	v_lshlrev_b32_e32 v88, 16, v83
	v_and_b32_e32 v89, 0xffff0000, v83
	v_ldexp_f32 v148, v44, v43
	v_add_u32_e32 v44, 21, v17
	v_lshlrev_b32_e32 v186, 16, v86
	v_and_b32_e32 v187, 0xffff0000, v86
	v_lshlrev_b32_e32 v86, 16, v82
	v_and_b32_e32 v87, 0xffff0000, v82
	v_lshlrev_b32_e32 v188, 16, v85
	v_and_b32_e32 v189, 0xffff0000, v85
	v_lshlrev_b32_e32 v82, 16, v81
	v_and_b32_e32 v83, 0xffff0000, v81
	v_lshlrev_b32_e32 v190, 16, v84
	v_and_b32_e32 v191, 0xffff0000, v84
	v_lshlrev_b32_e32 v84, 16, v80
	v_and_b32_e32 v85, 0xffff0000, v80
	v_lshlrev_b32_e32 v192, 16, v79
	v_and_b32_e32 v193, 0xffff0000, v79
	v_lshlrev_b32_e32 v80, 16, v75
	v_and_b32_e32 v81, 0xffff0000, v75
	v_lshlrev_b32_e32 v194, 16, v78
	v_and_b32_e32 v195, 0xffff0000, v78
	v_lshlrev_b32_e32 v78, 16, v74
	v_and_b32_e32 v79, 0xffff0000, v74
	v_lshlrev_b32_e32 v196, 16, v77
	v_and_b32_e32 v197, 0xffff0000, v77
	v_lshlrev_b32_e32 v74, 16, v73
	v_and_b32_e32 v75, 0xffff0000, v73
	v_lshlrev_b32_e32 v198, 16, v76
	v_and_b32_e32 v199, 0xffff0000, v76
	v_lshlrev_b32_e32 v76, 16, v72
	v_and_b32_e32 v77, 0xffff0000, v72
	v_lshlrev_b32_e32 v72, 16, v71
	v_and_b32_e32 v73, 0xffff0000, v71
	v_lshlrev_b32_e32 v214, 16, v67
	v_and_b32_e32 v215, 0xffff0000, v67
	v_lshlrev_b32_e32 v216, 16, v70
	v_and_b32_e32 v217, 0xffff0000, v70
	v_lshlrev_b32_e32 v70, 16, v66
	v_and_b32_e32 v71, 0xffff0000, v66
	v_lshlrev_b32_e32 v66, 16, v69
	v_and_b32_e32 v67, 0xffff0000, v69
	v_pk_fma_f32 v[68:69], v[222:223], v[222:223], v[68:69] op_sel_hi:[1,1,0]
	v_cvt_f32_i32_e32 v44, v44
	v_lshlrev_b32_e32 v220, 16, v65
	v_and_b32_e32 v221, 0xffff0000, v65
	v_lshlrev_b32_e32 v224, 16, v64
	v_and_b32_e32 v225, 0xffff0000, v64
	v_pk_fma_f32 v[64:65], v[66:67], v[66:67], v[68:69]
	v_mul_f32_e32 v68, v67, v67
	v_mul_f32_e32 v43, v148, v18
	v_pk_add_f32 v[64:65], v[68:69], v[64:65] op_sel_hi:[0,1]
	v_mul_f32_e32 v45, 0.15915494, v43
	v_pk_fma_f32 v[64:65], v[216:217], v[216:217], v[64:65]
	v_mul_f32_e32 v68, v217, v217
	v_floor_f32_e32 v45, v45
	v_pk_add_f32 v[64:65], v[68:69], v[64:65] op_sel_hi:[0,1]
	v_fma_f32 v43, v43, 0.15915494, -v45
	v_mul_f32_e32 v45, 0xbed49a78, v44
	v_pk_fma_f32 v[64:65], v[72:73], v[72:73], v[64:65]
	v_mul_f32_e32 v68, v73, v73
	v_cmp_gt_f32_e32 vcc, s36, v45
	v_pk_add_f32 v[64:65], v[68:69], v[64:65] op_sel_hi:[0,1]
	v_pk_fma_f32 v[64:65], v[198:199], v[198:199], v[64:65]
	v_cndmask_b32_e32 v45, 0, v208, vcc
; template <int NHQ, int NHKV>
; DI void attn_phase_l1(const u16* __restrict__ Q, const u16* __restrict__ K, const u16* __restrict__ Vt, u16* __restrict__ O, const float* __restrict__ qg, char* smem, const int wv) {
;     ...
;       float ssq = 0.f;
; #pragma unroll
;       for (int i = 0; i < NS; ++i) {
;         qf[i] = *(const bf16x8*)(qrow + 16 * i);
;         float t8[8]; unpack8(__builtin_bit_cast(u32x4, qf[i]), t8);
; #pragma unroll
;         for (int e = 0; e < 8; ++e) ssq += t8[e] * t8[e];
;       }
;       ssq = xhalf_sum(ssq);
;       const float rn = rsqrtf(ssq * (1.f / DQK) + EPS) * (0.08838834764831845f * 1.4426950408889634f);
;     ...
;       const float prow = (float)((pq - NMETA) >> 6), pcol = (float)((pq - NMETA) & 63);
;       A_QROPE(0, 2, 0, prow); A_QROPE(1, 3, 1, prow);
;       A_QROPE(4, 6, 0, pcol); A_QROPE(5, 7, 1, pcol);
	v_mul_f32_e32 v68, v199, v199
	v_fmac_f32_e32 v45, 0xbed49a78, v44
	v_pk_add_f32 v[64:65], v[68:69], v[64:65] op_sel_hi:[0,1]
	v_exp_f32_e32 v44, v45
	v_pk_fma_f32 v[64:65], v[196:197], v[196:197], v[64:65]
	v_mul_f32_e32 v68, v197, v197
	v_pk_add_f32 v[64:65], v[68:69], v[64:65] op_sel_hi:[0,1]
	v_pk_fma_f32 v[64:65], v[194:195], v[194:195], v[64:65]
	v_mul_f32_e32 v68, v195, v195
	v_sin_f32_e32 v112, v43
	v_cos_f32_e32 v114, v43
	v_cndmask_b32_e32 v43, 0, v209, vcc
	v_pk_add_f32 v[64:65], v[68:69], v[64:65] op_sel_hi:[0,1]
	v_ldexp_f32 v149, v44, v43
	v_add_u32_e32 v44, 22, v17
	v_pk_fma_f32 v[64:65], v[192:193], v[192:193], v[64:65]
	v_mul_f32_e32 v68, v193, v193
	v_cvt_f32_i32_e32 v44, v44
	v_pk_add_f32 v[64:65], v[68:69], v[64:65] op_sel_hi:[0,1]
	v_mul_f32_e32 v43, v149, v18
	v_pk_fma_f32 v[64:65], v[224:225], v[224:225], v[64:65]
	v_mul_f32_e32 v68, v225, v225
	v_mul_f32_e32 v45, 0.15915494, v43
	v_pk_add_f32 v[64:65], v[68:69], v[64:65] op_sel_hi:[0,1]
	v_floor_f32_e32 v45, v45
	v_pk_fma_f32 v[64:65], v[220:221], v[220:221], v[64:65]
	v_mul_f32_e32 v68, v221, v221
	v_fma_f32 v43, v43, 0.15915494, -v45
	v_mul_f32_e32 v45, 0xbed49a78, v44
	v_pk_add_f32 v[64:65], v[68:69], v[64:65] op_sel_hi:[0,1]
	v_cmp_gt_f32_e32 vcc, s36, v45
	v_pk_fma_f32 v[64:65], v[70:71], v[70:71], v[64:65]
	v_mul_f32_e32 v68, v71, v71
	v_cndmask_b32_e32 v45, 0, v208, vcc
	v_pk_add_f32 v[64:65], v[68:69], v[64:65] op_sel_hi:[0,1]
	v_fmac_f32_e32 v45, 0xbed49a78, v44
	v_pk_fma_f32 v[64:65], v[214:215], v[214:215], v[64:65]
	v_mul_f32_e32 v68, v215, v215
	v_exp_f32_e32 v44, v45
	v_pk_add_f32 v[64:65], v[68:69], v[64:65] op_sel_hi:[0,1]
	v_pk_fma_f32 v[64:65], v[76:77], v[76:77], v[64:65]
	v_mul_f32_e32 v68, v77, v77
	v_pk_add_f32 v[64:65], v[68:69], v[64:65] op_sel_hi:[0,1]
	v_sin_f32_e32 v113, v43
	v_cos_f32_e32 v115, v43
	v_cndmask_b32_e32 v43, 0, v209, vcc
	v_add_u32_e32 v17, 23, v17
	v_pk_fma_f32 v[64:65], v[74:75], v[74:75], v[64:65]
	v_mul_f32_e32 v68, v75, v75
	v_ldexp_f32 v152, v44, v43
	v_cvt_f32_i32_e32 v17, v17
	v_pk_add_f32 v[64:65], v[68:69], v[64:65] op_sel_hi:[0,1]
	v_mul_f32_e32 v43, v152, v18
	v_pk_fma_f32 v[64:65], v[78:79], v[78:79], v[64:65]
	v_mul_f32_e32 v68, v79, v79
	v_mul_f32_e32 v44, 0.15915494, v43
	v_pk_add_f32 v[64:65], v[68:69], v[64:65] op_sel_hi:[0,1]
	v_floor_f32_e32 v44, v44
	v_pk_fma_f32 v[64:65], v[80:81], v[80:81], v[64:65]
	v_mul_f32_e32 v68, v81, v81
	v_fma_f32 v43, v43, 0.15915494, -v44
	v_mul_f32_e32 v44, 0xbed49a78, v17
	v_pk_add_f32 v[64:65], v[68:69], v[64:65] op_sel_hi:[0,1]
	v_cmp_gt_f32_e32 vcc, s36, v44
	v_pk_fma_f32 v[64:65], v[190:191], v[190:191], v[64:65]
	v_mul_f32_e32 v68, v191, v191
	v_cndmask_b32_e32 v44, 0, v208, vcc
	v_pk_add_f32 v[64:65], v[68:69], v[64:65] op_sel_hi:[0,1]
	v_fmac_f32_e32 v44, 0xbed49a78, v17
	v_pk_fma_f32 v[64:65], v[188:189], v[188:189], v[64:65]
	v_mul_f32_e32 v68, v189, v189
	v_exp_f32_e32 v17, v44
	v_pk_add_f32 v[64:65], v[68:69], v[64:65] op_sel_hi:[0,1]
	v_pk_fma_f32 v[64:65], v[186:187], v[186:187], v[64:65]
	v_mul_f32_e32 v68, v187, v187
	v_pk_add_f32 v[64:65], v[68:69], v[64:65] op_sel_hi:[0,1]
	v_sin_f32_e32 v132, v43
	v_cos_f32_e32 v134, v43
	v_cndmask_b32_e32 v43, 0, v209, vcc
	v_pk_fma_f32 v[64:65], v[184:185], v[184:185], v[64:65]
	v_mul_f32_e32 v68, v185, v185
	v_ldexp_f32 v153, v17, v43
	v_pk_add_f32 v[64:65], v[68:69], v[64:65] op_sel_hi:[0,1]
	v_mul_f32_e32 v17, v153, v18
	v_pk_fma_f32 v[64:65], v[178:179], v[178:179], v[64:65]
	v_mul_f32_e32 v68, v179, v179
	v_mul_f32_e32 v18, 0.15915494, v17
	v_pk_add_f32 v[64:65], v[68:69], v[64:65] op_sel_hi:[0,1]
	v_floor_f32_e32 v18, v18
	v_pk_fma_f32 v[64:65], v[176:177], v[176:177], v[64:65]
	v_mul_f32_e32 v68, v177, v177
	v_fma_f32 v17, v17, 0.15915494, -v18
	v_pk_add_f32 v[64:65], v[68:69], v[64:65] op_sel_hi:[0,1]
	v_sin_f32_e32 v133, v17
	v_cos_f32_e32 v135, v17
	v_mul_f32_e32 v17, 0.15915494, v16
	v_pk_fma_f32 v[64:65], v[174:175], v[174:175], v[64:65]
	v_mul_f32_e32 v68, v175, v175
	v_floor_f32_e32 v17, v17
	v_pk_add_f32 v[64:65], v[68:69], v[64:65] op_sel_hi:[0,1]
	v_fma_f32 v16, v16, 0.15915494, -v17
	v_pk_fma_f32 v[64:65], v[158:159], v[158:159], v[64:65]
	v_mul_f32_e32 v68, v159, v159
	v_sin_f32_e32 v120, v16
	v_cos_f32_e32 v122, v16
	v_mul_f32_e32 v16, v20, v155
	v_pk_add_f32 v[64:65], v[68:69], v[64:65] op_sel_hi:[0,1]
	v_mul_f32_e32 v17, 0.15915494, v16
	v_pk_fma_f32 v[64:65], v[84:85], v[84:85], v[64:65]
	v_mul_f32_e32 v68, v85, v85
	v_floor_f32_e32 v17, v17
	v_pk_add_f32 v[64:65], v[68:69], v[64:65] op_sel_hi:[0,1]
	v_fma_f32 v16, v16, 0.15915494, -v17
	v_pk_fma_f32 v[64:65], v[82:83], v[82:83], v[64:65]
	v_mul_f32_e32 v68, v83, v83
	v_sin_f32_e32 v121, v16
	v_cos_f32_e32 v123, v16
	v_mul_f32_e32 v16, v21, v155
	v_pk_add_f32 v[64:65], v[68:69], v[64:65] op_sel_hi:[0,1]
	v_mul_f32_e32 v17, 0.15915494, v16
	v_pk_fma_f32 v[64:65], v[86:87], v[86:87], v[64:65]
	v_mul_f32_e32 v68, v87, v87
	v_floor_f32_e32 v17, v17
	v_pk_add_f32 v[64:65], v[68:69], v[64:65] op_sel_hi:[0,1]
	v_fma_f32 v16, v16, 0.15915494, -v17
	v_pk_fma_f32 v[64:65], v[88:89], v[88:89], v[64:65]
	v_mul_f32_e32 v68, v89, v89
	v_sin_f32_e32 v128, v16
	v_cos_f32_e32 v130, v16
	v_mul_f32_e32 v16, v22, v155
	v_pk_add_f32 v[64:65], v[68:69], v[64:65] op_sel_hi:[0,1]
	v_mul_f32_e32 v17, 0.15915494, v16
	v_pk_fma_f32 v[64:65], v[92:93], v[92:93], v[64:65]
	v_mul_f32_e32 v68, v93, v93
	v_floor_f32_e32 v17, v17
	v_pk_add_f32 v[64:65], v[68:69], v[64:65] op_sel_hi:[0,1]
	v_fma_f32 v16, v16, 0.15915494, -v17
	v_pk_fma_f32 v[64:65], v[90:91], v[90:91], v[64:65]
	v_mul_f32_e32 v68, v91, v91
	v_sin_f32_e32 v129, v16
	v_cos_f32_e32 v131, v16
	v_mul_f32_e32 v16, v23, v155
; #define B_LOADK(Kb_, tile_) do { const char* kp_ = (const char*)(Kb_) + (size_t)(tile_) * (64 * LDK * 2); const unsigned ko_ = ((tile_) == NT - 1) ? koffL : koff; \
;     _Pragma("unroll") for (int i_ = 0; i_ < NKC; ++i_) rk[i_] = *(const u32x4*)(kp_ + ko_ + i_ * 128); } while (0)
; #define B_LOADV(Vb_, tile_) do { const char* vp_ = (const char*)(Vb_) + (size_t)(tile_) * 128; \
;     rv[0] = *(const u32x4*)(vp_ + voff); rv[1] = *(const u32x4*)(vp_ + voff + 64 * LP * 2); } while (0)
; #define B_WRITEK(bi_) do { char* b_w = kb0 + (bi_) * KBYTES + kwoff; \
;     _Pragma("unroll") for (int i_ = 0; i_ < NKC; ++i_) *(u32x4*)(b_w + i_ * 128) = rk[i_]; } while (0)
; #define B_WRITEV(bi_) do { char* b_w = vb0 + (bi_) * VBYTES + vwoff; \
;     *(u32x4*)(b_w) = rv[0]; *(u32x4*)(b_w + 64 * VSTR) = rv[1]; } while (0)
; template <int NHQ, int NHKV>
; DI void attn_phase_l1(const u16* __restrict__ Q, const u16* __restrict__ K, const u16* __restrict__ Vt, u16* __restrict__ O, const float* __restrict__ qg, char* smem, const int wv) {
;     ...
;       ssq = xhalf_sum(ssq);
;       const float rn = rsqrtf(ssq * (1.f / DQK) + EPS) * (0.08838834764831845f * 1.4426950408889634f);
;     ...
;       const float prow = (float)((pq - NMETA) >> 6), pcol = (float)((pq - NMETA) & 63);
;       A_QROPE(0, 2, 0, prow); A_QROPE(1, 3, 1, prow);
;       A_QROPE(4, 6, 0, pcol); A_QROPE(5, 7, 1, pcol);
;     ...
;     }
;     float l = 0.f;
; #pragma unroll
;     for (int d = 0; d < 4; ++d)
; #pragma unroll
;       for (int i = 0; i < 16; ++i) o[d][i] = 0.f;
;     __syncthreads();
;     B_LOADK(Kb, 0); B_WRITEK(0); B_LOADK(Kb, 1); B_WRITEK(1); B_LOADV(Vb, 0); B_WRITEV(0);
;     B_LOADK(Kb, 2); B_LOADV(Vb, 1);
;     __syncthreads();
	v_pk_add_f32 v[64:65], v[68:69], v[64:65] op_sel_hi:[0,1]
	v_mul_f32_e32 v17, 0.15915494, v16
	v_pk_fma_f32 v[64:65], v[94:95], v[94:95], v[64:65]
	v_mul_f32_e32 v68, v95, v95
	v_floor_f32_e32 v17, v17
	v_pk_add_f32 v[64:65], v[68:69], v[64:65] op_sel_hi:[0,1]
	v_fma_f32 v16, v16, 0.15915494, -v17
	v_pk_fma_f32 v[64:65], v[156:157], v[156:157], v[64:65]
	v_mul_f32_e32 v68, v157, v157
	v_sin_f32_e32 v136, v16
	v_cos_f32_e32 v138, v16
	v_mul_f32_e32 v16, v40, v155
	v_pk_add_f32 v[64:65], v[68:69], v[64:65] op_sel_hi:[0,1]
	v_mul_f32_e32 v17, 0.15915494, v16
	v_mov_b32_e32 v65, v64
	v_floor_f32_e32 v17, v17
	s_nop 0
	v_permlane32_swap_b32_e32 v64, v65
	v_fma_f32 v16, v16, 0.15915494, -v17
	v_add_f32_e32 v64, v64, v65
	v_sin_f32_e32 v137, v16
	v_cos_f32_e32 v139, v16
	v_mul_f32_e32 v16, v41, v155
	v_fmamk_f32 v64, v64, 0x3c000000, v210
	v_mul_f32_e32 v17, 0.15915494, v16
	v_mul_f32_e32 v65, 0x4b800000, v64
	v_cmp_gt_f32_e32 vcc, s37, v64
	v_floor_f32_e32 v17, v17
	v_fma_f32 v16, v16, 0.15915494, -v17
	v_cndmask_b32_e32 v64, v64, v65, vcc
	v_mul_f32_e32 v153, v153, v155
	v_rsq_f32_e32 v64, v64
	v_sin_f32_e32 v116, v16
	v_cos_f32_e32 v118, v16
	v_mul_f32_e32 v16, v42, v155
	v_mul_f32_e32 v124, v124, v155
	v_mul_f32_e32 v125, v125, v155
	v_mul_f32_e32 v144, v144, v155
	v_mul_f32_e32 v145, v145, v155
	v_mul_f32_e32 v148, v148, v155
	v_mul_f32_e32 v149, v149, v155
	v_mul_f32_e32 v152, v152, v155
	v_mul_f32_e32 v155, 0.15915494, v153
	v_floor_f32_e32 v155, v155
	v_fma_f32 v65, v153, 0.15915494, -v155
	v_sin_f32_e32 v153, v65
	v_cos_f32_e32 v155, v65
	v_mul_f32_e32 v65, 0x45800000, v64
	v_cndmask_b32_e32 v64, v64, v65, vcc
	v_sin_f32_e32 v181, v0
	v_cos_f32_e32 v183, v0
	global_load_dwordx4 v[8:11], v[166:167], off offset:64
	global_load_dwordx4 v[0:3], v[166:167], off offset:80
	v_mul_f32_e32 v64, 0x3e0293ee, v64
	global_load_dwordx4 v[12:15], v[166:167], off offset:192
	global_load_dwordx4 v[4:7], v[166:167], off offset:208
	s_waitcnt vmcnt(7)
	v_pk_mul_f32 v[28:29], v[28:29], v[64:65] op_sel_hi:[1,0]
	v_pk_mul_f32 v[30:31], v[30:31], v[64:65] op_sel_hi:[1,0]
	v_pk_mul_f32 v[28:29], v[28:29], v[222:223]
	s_waitcnt vmcnt(5)
	v_pk_mul_f32 v[36:37], v[36:37], v[64:65] op_sel_hi:[1,0]
	v_pk_mul_f32 v[30:31], v[30:31], v[66:67]
	v_pk_mul_f32 v[36:37], v[36:37], v[224:225]
	v_pk_mul_f32 v[66:67], v[96:97], v[28:29]
	v_pk_mul_f32 v[38:39], v[38:39], v[64:65] op_sel_hi:[1,0]
	v_pk_fma_f32 v[66:67], v[98:99], v[36:37], v[66:67]
	v_pk_mul_f32 v[36:37], v[96:97], v[36:37]
	v_pk_mul_f32 v[24:25], v[24:25], v[64:65] op_sel_hi:[1,0]
	v_pk_mul_f32 v[38:39], v[38:39], v[220:221]
	v_pk_fma_f32 v[28:29], v[98:99], v[28:29], v[36:37] neg_lo:[0,0,1] neg_hi:[0,0,1]
	v_pk_mul_f32 v[36:37], v[100:101], v[30:31]
	v_pk_mul_f32 v[24:25], v[24:25], v[216:217]
	s_waitcnt vmcnt(4)
	v_pk_mul_f32 v[32:33], v[32:33], v[64:65] op_sel_hi:[1,0]
	v_pk_fma_f32 v[36:37], v[102:103], v[38:39], v[36:37]
	v_pk_mul_f32 v[38:39], v[100:101], v[38:39]
	v_pk_mul_f32 v[26:27], v[26:27], v[64:65] op_sel_hi:[1,0]
	v_pk_mul_f32 v[32:33], v[32:33], v[70:71]
	v_pk_fma_f32 v[30:31], v[102:103], v[30:31], v[38:39] neg_lo:[0,0,1] neg_hi:[0,0,1]
	v_pk_mul_f32 v[38:39], v[140:141], v[24:25]
	s_add_u32 s24, s24, s22
	global_load_dwordx4 v[60:63], v[166:167], off offset:256
	global_load_dwordx4 v[56:59], v[166:167], off offset:272
	global_load_dwordx4 v[52:55], v[166:167], off offset:384
	global_load_dwordx4 v[48:51], v[166:167], off offset:400
	v_pk_mul_f32 v[26:27], v[26:27], v[72:73]
	v_pk_mul_f32 v[34:35], v[34:35], v[64:65] op_sel_hi:[1,0]
	v_pk_fma_f32 v[98:99], v[142:143], v[32:33], v[38:39]
	v_pk_mul_f32 v[32:33], v[140:141], v[32:33]
	s_mul_i32 s26, s42, 0x2080
	s_addc_u32 s25, s25, s23
	v_pk_mul_f32 v[34:35], v[34:35], v[214:215]
	v_pk_fma_f32 v[24:25], v[142:143], v[24:25], v[32:33] neg_lo:[0,0,1] neg_hi:[0,0,1]
	v_pk_mul_f32 v[32:33], v[180:181], v[26:27]
	s_mul_hi_i32 s27, s42, 0x2080
	s_add_u32 s26, s31, s26
	v_pk_fma_f32 v[140:141], v[182:183], v[34:35], v[32:33]
	v_pk_mul_f32 v[32:33], v[180:181], v[34:35]
	v_lshl_add_u64 v[180:181], s[24:25], 0, v[160:161]
	s_addc_u32 s27, s34, s27
	v_pk_fma_f32 v[26:27], v[182:183], v[26:27], v[32:33] neg_lo:[0,0,1] neg_hi:[0,0,1]
	v_add_co_u32_e32 v32, vcc, s38, v180
	v_mul_f32_e32 v17, 0.15915494, v16
	s_nop 0
	v_addc_co_u32_e32 v33, vcc, 0, v181, vcc
	v_lshl_add_u64 v[142:143], s[26:27], 0, v[162:163]
	v_floor_f32_e32 v17, v17
	v_add_co_u32_e32 v182, vcc, s39, v142
	v_fma_f32 v16, v16, 0.15915494, -v17
	v_cvt_pk_bf16_f32 v97, v36, v37
	v_lshl_add_u64 v[36:37], v[180:181], 0, s[8:9]
	v_addc_co_u32_e32 v183, vcc, 0, v143, vcc
	v_sin_f32_e32 v117, v16
	v_cos_f32_e32 v119, v16
	global_load_dwordx4 v[44:47], v[166:167], off offset:320
	global_load_dwordx4 v[40:43], v[166:167], off offset:336
	global_load_dwordx4 v[20:23], v[166:167], off offset:448
	global_load_dwordx4 v[16:19], v[166:167], off offset:464
	v_cvt_pk_bf16_f32 v100, v28, v29
	v_cvt_pk_bf16_f32 v101, v30, v31
	v_cvt_pk_bf16_f32 v102, v24, v25
	v_cvt_pk_bf16_f32 v103, v26, v27
	v_cvt_pk_bf16_f32 v96, v66, v67
	s_barrier
; #define B_LOADK(Kb_, tile_) do { const char* kp_ = (const char*)(Kb_) + (size_t)(tile_) * (64 * LDK * 2); const unsigned ko_ = ((tile_) == NT - 1) ? koffL : koff; \
;     _Pragma("unroll") for (int i_ = 0; i_ < NKC; ++i_) rk[i_] = *(const u32x4*)(kp_ + ko_ + i_ * 128); } while (0)
; #define B_LOADV(Vb_, tile_) do { const char* vp_ = (const char*)(Vb_) + (size_t)(tile_) * 128; \
;     rv[0] = *(const u32x4*)(vp_ + voff); rv[1] = *(const u32x4*)(vp_ + voff + 64 * LP * 2); } while (0)
; #define B_WRITEK(bi_) do { char* b_w = kb0 + (bi_) * KBYTES + kwoff; \
;     _Pragma("unroll") for (int i_ = 0; i_ < NKC; ++i_) *(u32x4*)(b_w + i_ * 128) = rk[i_]; } while (0)
; #define B_WRITEV(bi_) do { char* b_w = vb0 + (bi_) * VBYTES + vwoff; \
;     *(u32x4*)(b_w) = rv[0]; *(u32x4*)(b_w + 64 * VSTR) = rv[1]; } while (0)
; template <int NHQ, int NHKV>
; DI void attn_phase_l1(const u16* __restrict__ Q, const u16* __restrict__ K, const u16* __restrict__ Vt, u16* __restrict__ O, const float* __restrict__ qg, char* smem, const int wv) {
;     ...
;       const float prow = (float)((pq - NMETA) >> 6), pcol = (float)((pq - NMETA) & 63);
;       A_QROPE(0, 2, 0, prow); A_QROPE(1, 3, 1, prow);
;       A_QROPE(4, 6, 0, pcol); A_QROPE(5, 7, 1, pcol);
;     ...
;     B_LOADK(Kb, 0); B_WRITEK(0); B_LOADK(Kb, 1); B_WRITEK(1); B_LOADV(Vb, 0); B_WRITEV(0);
;     B_LOADK(Kb, 2); B_LOADV(Vb, 1);
;     __syncthreads();
	global_load_dwordx4 v[24:27], v[180:181], off
	global_load_dwordx4 v[28:31], v[180:181], off offset:128
	s_nop 0
	global_load_dwordx4 v[32:35], v[32:33], off
	s_nop 0
	global_load_dwordx4 v[36:39], v[36:37], off offset:128
	v_cvt_pk_bf16_f32 v98, v98, v99
	global_load_dwordx4 v[66:69], v[142:143], off
	global_load_dwordx4 v[70:73], v[182:183], off
	s_waitcnt vmcnt(5)
	ds_write_b128 v203, v[24:27]
	s_waitcnt vmcnt(4)
	ds_write_b128 v203, v[28:31] offset:128
	s_waitcnt vmcnt(3)
	ds_write_b128 v203, v[32:35] offset:17408
	s_waitcnt vmcnt(2)
	ds_write_b128 v203, v[36:39] offset:17536
	v_pk_mul_f32 v[8:9], v[8:9], v[64:65] op_sel_hi:[1,0]
	v_pk_mul_f32 v[12:13], v[12:13], v[64:65] op_sel_hi:[1,0]
	v_pk_mul_f32 v[8:9], v[8:9], v[198:199]
	v_pk_mul_f32 v[14:15], v[14:15], v[64:65] op_sel_hi:[1,0]
	v_pk_mul_f32 v[10:11], v[10:11], v[64:65] op_sel_hi:[1,0]
	v_pk_mul_f32 v[12:13], v[12:13], v[76:77]
	v_pk_mul_f32 v[14:15], v[14:15], v[74:75]
	v_pk_mul_f32 v[74:75], v[104:105], v[8:9]
	v_pk_mul_f32 v[10:11], v[10:11], v[196:197]
	v_pk_fma_f32 v[74:75], v[106:107], v[12:13], v[74:75]
	v_pk_mul_f32 v[12:13], v[104:105], v[12:13]
	v_pk_mul_f32 v[0:1], v[0:1], v[64:65] op_sel_hi:[1,0]
	v_pk_fma_f32 v[8:9], v[106:107], v[8:9], v[12:13] neg_lo:[0,0,1] neg_hi:[0,0,1]
	v_pk_mul_f32 v[12:13], v[108:109], v[10:11]
	v_pk_mul_f32 v[0:1], v[0:1], v[194:195]
	v_pk_mul_f32 v[4:5], v[4:5], v[64:65] op_sel_hi:[1,0]
	v_pk_fma_f32 v[12:13], v[110:111], v[14:15], v[12:13]
	v_pk_mul_f32 v[14:15], v[108:109], v[14:15]
	v_pk_mul_f32 v[2:3], v[2:3], v[64:65] op_sel_hi:[1,0]
	v_pk_mul_f32 v[4:5], v[4:5], v[78:79]
	v_pk_fma_f32 v[10:11], v[110:111], v[10:11], v[14:15] neg_lo:[0,0,1] neg_hi:[0,0,1]
	v_pk_mul_f32 v[14:15], v[112:113], v[0:1]
	v_pk_mul_f32 v[2:3], v[2:3], v[192:193]
	v_pk_mul_f32 v[6:7], v[6:7], v[64:65] op_sel_hi:[1,0]
	v_pk_fma_f32 v[14:15], v[114:115], v[4:5], v[14:15]
	v_pk_mul_f32 v[4:5], v[112:113], v[4:5]
	v_pk_mul_f32 v[6:7], v[6:7], v[80:81]
	v_pk_fma_f32 v[0:1], v[114:115], v[0:1], v[4:5] neg_lo:[0,0,1] neg_hi:[0,0,1]
	v_pk_mul_f32 v[4:5], v[132:133], v[2:3]
	v_cvt_pk_bf16_f32 v108, v8, v9
	v_pk_mul_f32 v[8:9], v[64:65], v[52:53] op_sel_hi:[0,1]
	v_pk_fma_f32 v[4:5], v[134:135], v[6:7], v[4:5]
	v_cvt_pk_bf16_f32 v110, v0, v1
	v_cvt_pk_bf16_f32 v105, v12, v13
	v_pk_mul_f32 v[0:1], v[60:61], v[64:65] op_sel_hi:[1,0]
	v_pk_mul_f32 v[8:9], v[8:9], v[84:85]
	v_pk_mul_f32 v[12:13], v[64:65], v[54:55] op_sel_hi:[0,1]
	v_pk_mul_f32 v[6:7], v[132:133], v[6:7]
	v_cvt_pk_bf16_f32 v109, v10, v11
	v_cvt_pk_bf16_f32 v107, v4, v5
	v_pk_mul_f32 v[0:1], v[0:1], v[190:191]
	v_pk_mul_f32 v[4:5], v[62:63], v[64:65] op_sel_hi:[1,0]
	v_pk_mul_f32 v[10:11], v[64:65], v[48:49] op_sel_hi:[0,1]
	v_pk_mul_f32 v[12:13], v[12:13], v[82:83]
	v_pk_mul_f32 v[48:49], v[120:121], v[8:9]
	v_pk_mul_f32 v[8:9], v[122:123], v[8:9]
	v_pk_fma_f32 v[2:3], v[134:135], v[2:3], v[6:7] neg_lo:[0,0,1] neg_hi:[0,0,1]
	v_pk_mul_f32 v[4:5], v[4:5], v[188:189]
	v_pk_fma_f32 v[48:49], v[122:123], v[0:1], v[48:49] neg_lo:[0,0,1] neg_hi:[0,0,1]
	v_pk_fma_f32 v[8:9], v[120:121], v[0:1], v[8:9]
	v_pk_mul_f32 v[0:1], v[128:129], v[12:13]
	v_cvt_pk_bf16_f32 v111, v2, v3
	v_cvt_pk_bf16_f32 v106, v14, v15
	v_pk_mul_f32 v[2:3], v[64:65], v[56:57] op_sel_hi:[0,1]
	v_pk_mul_f32 v[10:11], v[10:11], v[86:87]
	v_pk_mul_f32 v[14:15], v[64:65], v[50:51] op_sel_hi:[0,1]
	v_pk_fma_f32 v[50:51], v[130:131], v[4:5], v[0:1] neg_lo:[0,0,1] neg_hi:[0,0,1]
	v_pk_mul_f32 v[0:1], v[130:131], v[12:13]
	v_pk_mul_f32 v[2:3], v[2:3], v[186:187]
	v_pk_fma_f32 v[52:53], v[128:129], v[4:5], v[0:1]
	v_pk_mul_f32 v[0:1], v[136:137], v[10:11]
	v_pk_mul_f32 v[6:7], v[64:65], v[58:59] op_sel_hi:[0,1]
	v_pk_mul_f32 v[14:15], v[14:15], v[88:89]
	v_pk_fma_f32 v[4:5], v[138:139], v[2:3], v[0:1] neg_lo:[0,0,1] neg_hi:[0,0,1]
	v_pk_mul_f32 v[0:1], v[138:139], v[10:11]
	v_pk_mul_f32 v[6:7], v[6:7], v[184:185]
	v_pk_fma_f32 v[54:55], v[136:137], v[2:3], v[0:1]
	v_pk_mul_f32 v[0:1], v[116:117], v[14:15]
	v_add_co_u32_e32 v2, vcc, s40, v180
	v_pk_fma_f32 v[10:11], v[118:119], v[6:7], v[0:1] neg_lo:[0,0,1] neg_hi:[0,0,1]
	s_waitcnt vmcnt(1)
	ds_write_b128 v204, v[66:69] offset:34816
	s_waitcnt vmcnt(0)
	ds_write_b128 v204, v[70:73] offset:44032
	v_lshl_add_u64 v[0:1], v[180:181], 0, s[14:15]
	v_addc_co_u32_e32 v3, vcc, 0, v181, vcc
	v_cvt_pk_bf16_f32 v99, v140, v141
	global_load_dwordx4 v[136:139], v[142:143], off offset:128
	v_pk_mul_f32 v[12:13], v[118:119], v[14:15]
	global_load_dwordx4 v[140:143], v[182:183], off offset:128
	global_load_dwordx4 v[128:131], v[2:3], off
	global_load_dwordx4 v[132:135], v[0:1], off offset:128
	s_waitcnt lgkmcnt(0)
	s_barrier
; DI unsigned cvtpk(float lo, float hi) { f32x2 v = {lo, hi}; return __builtin_bit_cast(unsigned, __builtin_convertvector(v, bf16x2_t)); }
; template <int NHQ, int NHKV>
; DI void attn_phase_l1(const u16* __restrict__ Q, const u16* __restrict__ K, const u16* __restrict__ Vt, u16* __restrict__ O, const float* __restrict__ qg, char* smem, const int wv) {
;     ...
;     {
;       const char* sk = kb0 + r32 * KSTR + hh * 16;
; #pragma unroll
;       for (int i = 0; i < 16; ++i) { s0[i] = 0.f; s1[i] = 0.f; }
; #pragma unroll
;       for (int i = 0; i < NS; ++i) {
;         const bf16x8 k0f = *(const bf16x8*)(sk + i * 32), k1f = *(const bf16x8*)(sk + 32 * KSTR + i * 32);
;         s0 = __builtin_amdgcn_mfma_f32_32x32x16_bf16(k0f, qf[i], s0, 0, 0, 0);
;         s1 = __builtin_amdgcn_mfma_f32_32x32x16_bf16(k1f, qf[i], s1, 0, 0, 0);
;       }
;       unsigned w_[16]; f32x2 ps2 = {0.f, 0.f};
; #pragma unroll
;       for (int i = 0; i < 8; ++i) { f32x2 v; v[0] = __builtin_amdgcn_exp2f(s0[2 * i]); v[1] = __builtin_amdgcn_exp2f(s0[2 * i + 1]); ps2 += v; w_[i] = cvtpk(v[0], v[1]); }
; #pragma unroll
;       for (int i = 0; i < 8; ++i) { f32x2 v; v[0] = __builtin_amdgcn_exp2f(s1[2 * i]); v[1] = __builtin_amdgcn_exp2f(s1[2 * i + 1]); ps2 += v; w_[8 + i] = cvtpk(v[0], v[1]); }
;       l += ps2[0] + ps2[1];
; #pragma unroll
;       for (int q = 0; q < 4; ++q) pb[q] = __builtin_bit_cast(bf16x8, u32x4{w_[4 * q], w_[4 * q + 1], w_[4 * q + 2], w_[4 * q + 3]});
;     }
	ds_read_b128 v[0:3], v205
	ds_read_b128 v[24:27], v205 offset:32
	v_pk_fma_f32 v[32:33], v[116:117], v[6:7], v[12:13]
	v_cvt_pk_bf16_f32 v118, v4, v5
	v_cvt_pk_bf16_f32 v119, v10, v11
	v_cvt_pk_bf16_f32 v112, v8, v9
	s_waitcnt lgkmcnt(1)
	v_mfma_f32_32x32x16_bf16 v[0:15], v[0:3], v[100:103], 0
	v_mul_f32_e64 v28, v64, v44
	v_mul_f32_e64 v29, v64, v45
	v_mul_f32_e64 v34, v28, v178
	v_mul_f32_e64 v35, v29, v179
	v_mul_f32_e64 v28, v64, v40
	v_mul_f32_e64 v29, v64, v41
	v_pk_mul_f32 v[36:37], v[28:29], v[174:175]
	ds_read_b128 v[28:31], v205 offset:64
	v_pk_mul_f32 v[16:17], v[64:65], v[16:17] op_sel_hi:[0,1]
	v_mul_f32_e32 v126, 0.15915494, v124
	s_waitcnt lgkmcnt(1)
	v_mfma_f32_32x32x16_bf16 v[0:15], v[24:27], v[108:111], v[0:15]
	v_mul_f32_e64 v24, v64, v46
	v_mul_f32_e64 v25, v64, v47
	v_mul_f32_e64 v38, v24, v176
	v_mul_f32_e64 v39, v25, v177
	v_mul_f32_e64 v24, v64, v42
	v_mul_f32_e64 v25, v64, v43
	v_pk_mul_f32 v[40:41], v[24:25], v[158:159]
	ds_read_b128 v[24:27], v205 offset:96
	v_mul_f32_e32 v127, 0.15915494, v125
	v_floor_f32_e32 v126, v126
	s_waitcnt lgkmcnt(1)
	v_mfma_f32_32x32x16_bf16 v[0:15], v[28:31], v[96:99], v[0:15]
	v_mul_f32_e64 v28, v16, v94
	v_mul_f32_e64 v29, v17, v95
	v_mul_f32_e64 v16, v64, v22
	v_mul_f32_e64 v17, v64, v23
	v_floor_f32_e32 v127, v127
	v_mul_f32_e32 v146, 0.15915494, v144
	v_mul_f32_e32 v147, 0.15915494, v145
	v_pk_mul_f32 v[30:31], v[16:17], v[90:91]
	v_pk_mul_f32 v[16:17], v[64:65], v[18:19] op_sel_hi:[0,1]
	v_fma_f32 v126, v124, 0.15915494, -v126
	v_fma_f32 v127, v125, 0.15915494, -v127
	v_floor_f32_e32 v146, v146
	v_floor_f32_e32 v147, v147
	v_mul_f32_e32 v150, 0.15915494, v148
	v_mul_f32_e32 v151, 0.15915494, v149
	v_cvt_pk_bf16_f32 v104, v74, v75
	v_pk_mul_f32 v[44:45], v[16:17], v[156:157]
	ds_read_b128 v[16:19], v205 offset:128
	v_sin_f32_e32 v124, v126
	v_sin_f32_e32 v125, v127
	v_fma_f32 v146, v144, 0.15915494, -v146
	v_fma_f32 v147, v145, 0.15915494, -v147
	v_floor_f32_e32 v150, v150
	v_floor_f32_e32 v151, v151
	s_waitcnt lgkmcnt(1)
	v_mfma_f32_32x32x16_bf16 v[0:15], v[24:27], v[104:107], v[0:15]
	v_cos_f32_e32 v126, v126
	v_cos_f32_e32 v127, v127
	v_sin_f32_e32 v144, v146
	v_sin_f32_e32 v145, v147
	v_fma_f32 v150, v148, 0.15915494, -v150
	v_fma_f32 v151, v149, 0.15915494, -v151
	v_cos_f32_e32 v146, v146
	v_cos_f32_e32 v147, v147
	v_sin_f32_e32 v148, v150
	v_sin_f32_e32 v149, v151
	v_pk_mul_f32 v[20:21], v[64:65], v[20:21] op_sel_hi:[0,1]
	v_cos_f32_e32 v150, v150
	v_cos_f32_e32 v151, v151
	v_pk_mul_f32 v[42:43], v[20:21], v[92:93]
	v_mul_f32_e32 v154, 0.15915494, v152
	v_pk_mul_f32 v[20:21], v[124:125], v[42:43]
	v_floor_f32_e32 v154, v154
	v_pk_fma_f32 v[24:25], v[126:127], v[34:35], v[20:21] neg_lo:[0,0,1] neg_hi:[0,0,1]
	v_pk_mul_f32 v[20:21], v[144:145], v[30:31]
	v_cvt_pk_bf16_f32 v116, v48, v49
	v_pk_fma_f32 v[26:27], v[146:147], v[38:39], v[20:21] neg_lo:[0,0,1] neg_hi:[0,0,1]
	v_pk_mul_f32 v[20:21], v[148:149], v[28:29]
	v_cvt_pk_bf16_f32 v117, v50, v51
	v_pk_fma_f32 v[46:47], v[150:151], v[36:37], v[20:21] neg_lo:[0,0,1] neg_hi:[0,0,1]
	ds_read_b128 v[20:23], v205 offset:160
	v_fma_f32 v154, v152, 0.15915494, -v154
	s_waitcnt lgkmcnt(1)
	v_mfma_f32_32x32x16_bf16 v[0:15], v[16:19], v[116:119], v[0:15]
	v_sin_f32_e32 v152, v154
	v_cos_f32_e32 v154, v154
	v_cvt_pk_bf16_f32 v120, v24, v25
	v_cvt_pk_bf16_f32 v121, v26, v27
	v_pk_mul_f32 v[16:17], v[152:153], v[44:45]
	v_cvt_pk_bf16_f32 v122, v46, v47
	v_pk_fma_f32 v[16:17], v[154:155], v[40:41], v[16:17] neg_lo:[0,0,1] neg_hi:[0,0,1]
	v_cvt_pk_bf16_f32 v113, v52, v53
	v_cvt_pk_bf16_f32 v123, v16, v17
	ds_read_b128 v[16:19], v205 offset:192
	v_cvt_pk_bf16_f32 v114, v54, v55
	s_waitcnt lgkmcnt(1)
	v_mfma_f32_32x32x16_bf16 v[0:15], v[20:23], v[120:123], v[0:15]
	v_mul_f32_e64 v20, v126, v42
	v_mul_f32_e64 v21, v127, v43
	v_cvt_pk_bf16_f32 v115, v32, v33
	v_fma_f32 v24, v124, v34, v20
	v_fma_f32 v25, v125, v35, v21
	v_pk_mul_f32 v[20:21], v[146:147], v[30:31]
	v_pk_mul_f32 v[28:29], v[150:151], v[28:29]
	v_pk_fma_f32 v[26:27], v[144:145], v[38:39], v[20:21]
	ds_read_b128 v[20:23], v205 offset:224
	s_waitcnt lgkmcnt(1)
	v_mfma_f32_32x32x16_bf16 v[0:15], v[16:19], v[112:115], v[0:15]
	v_mul_f32_e64 v18, v154, v44
	v_mul_f32_e64 v19, v155, v45
	v_fma_f32 v16, v148, v36, v28
	v_fma_f32 v17, v149, v37, v29
	v_fma_f32 v18, v152, v40, v18
	v_fma_f32 v19, v153, v41, v19
	v_cvt_pk_bf16_f32 v126, v16, v17
	v_cvt_pk_bf16_f32 v127, v18, v19
	ds_read_b128 v[16:19], v205 offset:8704
	ds_read_b128 v[32:35], v205 offset:8736
	v_cvt_pk_bf16_f32 v124, v24, v25
	v_cvt_pk_bf16_f32 v125, v26, v27
	v_mad_i64_i32 v[174:175], s[24:25], s42, v212, v[162:163]
	s_waitcnt lgkmcnt(2)
	v_mfma_f32_32x32x16_bf16 v[0:15], v[20:23], v[124:127], v[0:15]
	s_add_u32 s24, s20, s22
	s_addc_u32 s25, s21, s23
	s_mov_b32 s42, -1
	v_mov_b32_e32 v50, v165
	v_mov_b32_e32 v51, v165
	v_mov_b32_e32 v52, v165
	v_mov_b32_e32 v53, v165
	s_waitcnt lgkmcnt(1)
	v_mfma_f32_32x32x16_bf16 v[16:31], v[16:19], v[100:103], 0
	s_nop 2
	v_exp_f32_e32 v44, v0
	v_exp_f32_e32 v45, v1
	v_exp_f32_e32 v46, v2
	v_exp_f32_e32 v47, v3
	v_exp_f32_e32 v4, v4
	v_exp_f32_e32 v5, v5
	v_exp_f32_e32 v6, v6
	s_waitcnt lgkmcnt(0)
	v_mfma_f32_32x32x16_bf16 v[16:31], v[32:35], v[108:111], v[16:31]
	ds_read_b128 v[32:35], v205 offset:8768
	ds_read_b128 v[36:39], v205 offset:8800
	v_exp_f32_e32 v7, v7
	v_pk_add_f32 v[48:49], v[44:45], 0 op_sel_hi:[1,0]
	v_cvt_pk_bf16_f32 v80, v44, v45
	v_pk_add_f32 v[44:45], v[46:47], v[48:49]
	v_exp_f32_e32 v8, v8
	v_exp_f32_e32 v9, v9
	s_waitcnt lgkmcnt(1)
	v_mfma_f32_32x32x16_bf16 v[16:31], v[32:35], v[96:99], v[16:31]
	ds_read_b128 v[32:35], v205 offset:8832
	ds_read_b128 v[40:43], v205 offset:8864
	v_exp_f32_e32 v10, v10
	v_exp_f32_e32 v11, v11
	v_cvt_pk_bf16_f32 v146, v4, v5
	v_cvt_pk_bf16_f32 v147, v6, v7
	v_cvt_pk_bf16_f32 v145, v46, v47
	v_cvt_pk_bf16_f32 v84, v8, v9
	s_waitcnt lgkmcnt(2)
	v_mfma_f32_32x32x16_bf16 v[16:31], v[36:39], v[104:107], v[16:31]
	ds_read_b128 v[0:3], v205 offset:8896
	ds_read_b128 v[36:39], v205 offset:8928
	s_waitcnt lgkmcnt(0)
	s_barrier
; template <int NHQ, int NHKV>
; DI void attn_phase_l1(const u16* __restrict__ Q, const u16* __restrict__ K, const u16* __restrict__ Vt, u16* __restrict__ O, const float* __restrict__ qg, char* smem, const int wv) {
;     ...
;     float l = 0.f;
; #pragma unroll
;     for (int d = 0; d < 4; ++d)
; #pragma unroll
;       for (int i = 0; i < 16; ++i) o[d][i] = 0.f;
;     __syncthreads();
;     B_LOADK(Kb, 0); B_WRITEK(0); B_LOADK(Kb, 1); B_WRITEK(1); B_LOADV(Vb, 0); B_WRITEV(0);
;     B_LOADK(Kb, 2); B_LOADV(Vb, 1);
;     __syncthreads();
;     {
;       const char* sk = kb0 + r32 * KSTR + hh * 16;
; #pragma unroll
;       for (int i = 0; i < 16; ++i) { s0[i] = 0.f; s1[i] = 0.f; }
; #pragma unroll
;       for (int i = 0; i < NS; ++i) {
;         const bf16x8 k0f = *(const bf16x8*)(sk + i * 32), k1f = *(const bf16x8*)(sk + 32 * KSTR + i * 32);
;         s0 = __builtin_amdgcn_mfma_f32_32x32x16_bf16(k0f, qf[i], s0, 0, 0, 0);
;         s1 = __builtin_amdgcn_mfma_f32_32x32x16_bf16(k1f, qf[i], s1, 0, 0, 0);
;       }
;       unsigned w_[16]; f32x2 ps2 = {0.f, 0.f};
; #pragma unroll
;       for (int i = 0; i < 8; ++i) { f32x2 v; v[0] = __builtin_amdgcn_exp2f(s0[2 * i]); v[1] = __builtin_amdgcn_exp2f(s0[2 * i + 1]); ps2 += v; w_[i] = cvtpk(v[0], v[1]); }
; #pragma unroll
;       for (int i = 0; i < 8; ++i) { f32x2 v; v[0] = __builtin_amdgcn_exp2f(s1[2 * i]); v[1] = __builtin_amdgcn_exp2f(s1[2 * i + 1]); ps2 += v; w_[8 + i] = cvtpk(v[0], v[1]); }
;       l += ps2[0] + ps2[1];
; #pragma unroll
;       for (int q = 0; q < 4; ++q) pb[q] = __builtin_bit_cast(bf16x8, u32x4{w_[4 * q], w_[4 * q + 1], w_[4 * q + 2], w_[4 * q + 3]});
;     }
;     ...
;         unsigned w_[16]; f32x2 ps2 = {0.f, 0.f};
;     ...
; #pragma unroll
;         for (int i = 0; i < 16; ++i) { s0[i] = 0.f; s1[i] = 0.f; }
; #pragma unroll
;         for (int i = 0; i < RING; ++i) B_FRAG(ring[i], i);
; #pragma unroll
;         for (int i = 0; i < NM; ++i) {
;           if (i < NQK) {
;             if (i & 1) s1 = __builtin_amdgcn_mfma_f32_32x32x16_bf16(ring[i % RING], qf[i >> 1], s1, 0, 0, 0);
;             else       s0 = __builtin_amdgcn_mfma_f32_32x32x16_bf16(ring[i % RING], qf[i >> 1], s0, 0, 0, 0);
;           } else {
;             o[(i - NQK) & 3] = __builtin_amdgcn_mfma_f32_32x32x16_bf16(ring[i % RING], pb[(i - NQK) >> 2], o[(i - NQK) & 3], 0, 0, 0);
;           }
	v_cvt_pk_bf16_f32 v149, v10, v11
	v_mov_b32_e32 v48, v165
	v_mov_b32_e32 v49, v165
	s_waitcnt lgkmcnt(3)
	v_mfma_f32_32x32x16_bf16 v[16:31], v[32:35], v[116:119], v[16:31]
	v_add_f32_e64 v32, v4, v44
	v_add_f32_e64 v33, v5, v45
	v_mov_b32_e32 v54, v165
	v_add_f32_e64 v4, v6, v32
	v_add_f32_e64 v5, v7, v33
	v_exp_f32_e32 v6, v12
	v_exp_f32_e32 v7, v13
	v_pk_add_f32 v[4:5], v[8:9], v[4:5]
	v_mov_b32_e32 v55, v165
	s_waitcnt lgkmcnt(2)
	v_mfma_f32_32x32x16_bf16 v[16:31], v[40:43], v[120:123], v[16:31]
	v_add_f32_e64 v4, v10, v4
	v_add_f32_e64 v5, v11, v5
	v_cvt_pk_bf16_f32 v150, v6, v7
	v_mov_b32_e32 v56, v165
	v_mov_b32_e32 v57, v165
	v_mov_b32_e32 v58, v165
	v_mov_b32_e32 v59, v165
	v_mov_b32_e32 v60, v165
	s_waitcnt lgkmcnt(1)
	v_mfma_f32_32x32x16_bf16 v[16:31], v[0:3], v[112:115], v[16:31]
	v_exp_f32_e32 v0, v14
	v_exp_f32_e32 v1, v15
	v_pk_add_f32 v[2:3], v[6:7], v[4:5]
	v_mov_b32_e32 v61, v165
	v_mov_b32_e32 v62, v165
	v_pk_add_f32 v[2:3], v[0:1], v[2:3]
	v_cvt_pk_bf16_f32 v151, v0, v1
	s_waitcnt lgkmcnt(0)
	v_mfma_f32_32x32x16_bf16 v[16:31], v[36:39], v[124:127], v[16:31]
	v_mov_b32_e32 v63, v165
	v_mov_b32_e32 v32, v165
	v_mov_b32_e32 v33, v165
	v_mov_b32_e32 v34, v165
	v_mov_b32_e32 v35, v165
	v_mov_b32_e32 v36, v165
	v_mov_b32_e32 v37, v165
	s_nop 4
	v_exp_f32_e32 v4, v16
	v_exp_f32_e32 v5, v17
	v_exp_f32_e32 v6, v18
	v_exp_f32_e32 v7, v19
	v_mov_b32_e32 v38, v165
	v_pk_add_f32 v[0:1], v[2:3], v[4:5]
	v_exp_f32_e32 v2, v20
	v_exp_f32_e32 v3, v21
	v_cvt_pk_bf16_f32 v88, v4, v5
	v_pk_add_f32 v[0:1], v[6:7], v[0:1]
	v_exp_f32_e32 v4, v22
	v_exp_f32_e32 v5, v23
	v_pk_add_f32 v[0:1], v[2:3], v[0:1]
	v_cvt_pk_bf16_f32 v154, v2, v3
	v_exp_f32_e32 v2, v24
	v_exp_f32_e32 v3, v25
	v_cvt_pk_bf16_f32 v153, v6, v7
	v_pk_add_f32 v[0:1], v[4:5], v[0:1]
	v_exp_f32_e32 v6, v26
	v_exp_f32_e32 v7, v27
	v_pk_add_f32 v[0:1], v[2:3], v[0:1]
	v_cvt_pk_bf16_f32 v92, v2, v3
	v_exp_f32_e32 v2, v28
	v_exp_f32_e32 v3, v29
	v_cvt_pk_bf16_f32 v155, v4, v5
	v_exp_f32_e32 v4, v30
	v_exp_f32_e32 v5, v31
	v_pk_add_f32 v[0:1], v[6:7], v[0:1]
	v_cvt_pk_bf16_f32 v157, v6, v7
	v_pk_add_f32 v[0:1], v[2:3], v[0:1]
	v_cvt_pk_bf16_f32 v158, v2, v3
	v_pk_add_f32 v[0:1], v[4:5], v[0:1]
	v_cvt_pk_bf16_f32 v159, v4, v5
	v_add_f32_e32 v0, v0, v1
	v_add_f32_e32 v176, 0, v0
	v_mov_b32_e32 v39, v165
	v_mov_b32_e32 v40, v165
	v_mov_b32_e32 v41, v165
	v_mov_b32_e32 v42, v165
	v_mov_b32_e32 v43, v165
	v_mov_b32_e32 v44, v165
	v_mov_b32_e32 v45, v165
	v_mov_b32_e32 v46, v165
	v_mov_b32_e32 v47, v165
	v_mov_b32_e32 v16, v165
	v_mov_b32_e32 v17, v165
	v_mov_b32_e32 v18, v165
	v_mov_b32_e32 v19, v165
	v_mov_b32_e32 v20, v165
	v_mov_b32_e32 v21, v165
	v_mov_b32_e32 v22, v165
	v_mov_b32_e32 v23, v165
	v_mov_b32_e32 v24, v165
	v_mov_b32_e32 v25, v165
	v_mov_b32_e32 v26, v165
	v_mov_b32_e32 v27, v165
	v_mov_b32_e32 v28, v165
	v_mov_b32_e32 v29, v165
	v_mov_b32_e32 v30, v165
	v_mov_b32_e32 v31, v165
	v_mov_b32_e32 v0, v165
	v_mov_b32_e32 v1, v165
	v_mov_b32_e32 v2, v165
	v_mov_b32_e32 v3, v165
	v_mov_b32_e32 v4, v165
	v_mov_b32_e32 v5, v165
	v_mov_b32_e32 v6, v165
	v_mov_b32_e32 v7, v165
	v_mov_b32_e32 v8, v165
	v_mov_b32_e32 v9, v165
	v_mov_b32_e32 v10, v165
	v_mov_b32_e32 v11, v165
	v_mov_b32_e32 v12, v165
	v_mov_b32_e32 v13, v165
	v_mov_b32_e32 v14, v165
	v_mov_b32_e32 v15, v165
	s_cmp_ge_u32 s3, 4
	s_cbranch_scc1 .Lb_first
	v_mov_b32_e32 v156, v92
	v_mov_b32_e32 v152, v88
	s_add_i32 s27, s42, 1
	s_bitcmp1_b32 s27, 0
	s_cselect_b64 s[20:21], -1, 0
	s_and_b64 s[22:23], s[20:21], exec
	s_cselect_b32 s26, 0x4400, 0
	s_bitcmp1_b32 s42, 0
	s_cselect_b64 s[22:23], -1, 0
	s_and_b64 s[44:45], s[22:23], exec
	s_cselect_b32 s43, 0x4800, 0
	s_and_b64 s[22:23], s[22:23], exec
	s_cselect_b32 s22, 0x4400, 0
	v_add_u32_e32 v164, s22, v205
	ds_read_b128 v[246:249], v164
	ds_read_b128 v[178:181], v164 offset:32
	ds_read_b128 v[182:185], v164 offset:8736
	ds_read_b128 v[186:189], v164 offset:8768
	ds_read_b128 v[190:193], v164 offset:64
	ds_read_b128 v[194:197], v164 offset:96
	ds_read_b128 v[214:217], v164 offset:8800
	v_mov_b32_e32 v148, v84
	v_mov_b32_e32 v144, v80
	s_branch .La_body
	.p2align 3
.LBB0_1217:
	s_add_i32 s27, s42, 1
	s_bitcmp1_b32 s27, 0
	s_cselect_b64 s[20:21], -1, 0
	s_and_b64 s[22:23], s[20:21], exec
	s_cselect_b32 s26, 0x4400, 0
	s_bitcmp1_b32 s42, 0
	s_cselect_b64 s[22:23], -1, 0
	s_and_b64 s[44:45], s[22:23], exec
	s_cselect_b32 s43, 0x4800, 0
	s_and_b64 s[22:23], s[22:23], exec
	s_cselect_b32 s22, 0x4400, 0
	v_add_u32_e32 v164, s22, v205
	ds_read_b128 v[246:249], v164
	ds_read_b128 v[178:181], v164 offset:32
	ds_read_b128 v[182:185], v164 offset:8736
	ds_read_b128 v[186:189], v164 offset:8768
	ds_read_b128 v[190:193], v164 offset:64
	ds_read_b128 v[194:197], v164 offset:96
	ds_read_b128 v[214:217], v164 offset:8800
	v_exp_f32_e32 v250, v64
	v_exp_f32_e32 v251, v65
	s_nop 0
	v_add_f32_e32 v254, 0, v250
	v_add_f32_e32 v255, 0, v251
	v_exp_f32_e32 v252, v66
	v_exp_f32_e32 v253, v67
	v_cvt_pk_bf16_f32 v152, v250, v251
	v_add_f32_e32 v254, v252, v254
	v_add_f32_e32 v255, v253, v255
	v_exp_f32_e32 v250, v68
	v_exp_f32_e32 v251, v69
	v_cvt_pk_bf16_f32 v153, v252, v253
	v_add_f32_e32 v254, v250, v254
	v_add_f32_e32 v255, v251, v255
	v_exp_f32_e32 v252, v70
	v_exp_f32_e32 v253, v71
	v_cvt_pk_bf16_f32 v154, v250, v251
	v_add_f32_e32 v254, v252, v254
	v_add_f32_e32 v255, v253, v255
	v_exp_f32_e32 v250, v72
	v_exp_f32_e32 v251, v73
	v_cvt_pk_bf16_f32 v155, v252, v253
	v_add_f32_e32 v254, v250, v254
	v_add_f32_e32 v255, v251, v255
	v_exp_f32_e32 v252, v74
	v_exp_f32_e32 v253, v75
	v_cvt_pk_bf16_f32 v156, v250, v251
	v_add_f32_e32 v254, v252, v254
	v_add_f32_e32 v255, v253, v255
	v_exp_f32_e32 v250, v76
	v_exp_f32_e32 v251, v77
	v_cvt_pk_bf16_f32 v157, v252, v253
	v_add_f32_e32 v254, v250, v254
	v_add_f32_e32 v255, v251, v255
	v_exp_f32_e32 v252, v78
	v_exp_f32_e32 v253, v79
	v_cvt_pk_bf16_f32 v158, v250, v251
	v_add_f32_e32 v254, v252, v254
	v_add_f32_e32 v255, v253, v255
	v_cvt_pk_bf16_f32 v159, v252, v253
	v_add_f32_e32 v254, v254, v255
	v_add_f32_e32 v176, v176, v254
	v_mov_b32_e32 v148, v84
	v_mov_b32_e32 v144, v80
; #define B_LOADK(Kb_, tile_) do { const char* kp_ = (const char*)(Kb_) + (size_t)(tile_) * (64 * LDK * 2); const unsigned ko_ = ((tile_) == NT - 1) ? koffL : koff; \
;     _Pragma("unroll") for (int i_ = 0; i_ < NKC; ++i_) rk[i_] = *(const u32x4*)(kp_ + ko_ + i_ * 128); } while (0)
; #define B_LOADV(Vb_, tile_) do { const char* vp_ = (const char*)(Vb_) + (size_t)(tile_) * 128; \
;     rv[0] = *(const u32x4*)(vp_ + voff); rv[1] = *(const u32x4*)(vp_ + voff + 64 * LP * 2); } while (0)
; #define B_WRITEK(bi_) do { char* b_w = kb0 + (bi_) * KBYTES + kwoff; \
;     _Pragma("unroll") for (int i_ = 0; i_ < NKC; ++i_) *(u32x4*)(b_w + i_ * 128) = rk[i_]; } while (0)
; #define B_WRITEV(bi_) do { char* b_w = vb0 + (bi_) * VBYTES + vwoff; \
;     *(u32x4*)(b_w) = rv[0]; *(u32x4*)(b_w + 64 * VSTR) = rv[1]; } while (0)
; #define B_FRAG(dst_, i_) do { if ((i_) < NQK) { dst_ = *(const bf16x8*)(sk + ((i_) & 1) * (32 * KSTR) + ((i_) >> 1) * 32); } \
;           else { dst_ = *(const bf16x8*)(sv + (((i_) - NQK) & 3) * (32 * VSTR) + (((i_) - NQK) >> 2) * 32); } } while (0)
; template <int NHQ, int NHKV>
; DI void attn_phase_l1(const u16* __restrict__ Q, const u16* __restrict__ K, const u16* __restrict__ Vt, u16* __restrict__ O, const float* __restrict__ qg, char* smem, const int wv) {
;     ...
;       if (j + 2 < NT) B_WRITEK(j & 1);
;       if (j + 1 < NT) B_WRITEV((j + 1) & 1);
;       __builtin_amdgcn_sched_barrier(0);
;       if (j + 3 < NT) B_LOADK(Kb, j + 3);
;       if (j + 2 < NT) B_LOADV(Vb, j + 2);
;     ...
;         for (int i = 0; i < NM; ++i) {
;           if (i < NQK) {
;             if (i & 1) s1 = __builtin_amdgcn_mfma_f32_32x32x16_bf16(ring[i % RING], qf[i >> 1], s1, 0, 0, 0);
;             else       s0 = __builtin_amdgcn_mfma_f32_32x32x16_bf16(ring[i % RING], qf[i >> 1], s0, 0, 0, 0);
;           } else {
;             o[(i - NQK) & 3] = __builtin_amdgcn_mfma_f32_32x32x16_bf16(ring[i % RING], pb[(i - NQK) >> 2], o[(i - NQK) & 3], 0, 0, 0);
;           }
;           if (i + RING < NM) B_FRAG(ring[i % RING], i + RING);
.La_body:
	s_waitcnt lgkmcnt(6)
	v_mfma_f32_32x32x16_bf16 v[80:95], v[246:249], v[100:103], 0
	ds_read_b128 v[68:71], v164 offset:8704
	ds_read_b128 v[220:223], v164 offset:128
	s_and_b64 s[20:21], s[20:21], exec
	s_cselect_b32 s20, 0x4800, 0
	v_add_u32_e32 v177, s20, v206
	ds_read_b128 v[224:227], v164 offset:8832
	s_waitcnt lgkmcnt(2)
	v_mfma_f32_32x32x16_bf16 v[64:79], v[68:71], v[100:103], 0
	v_mfma_f32_32x32x16_bf16 v[80:95], v[178:181], v[108:111], v[80:95]
	ds_read_b128 v[228:231], v164 offset:160
	ds_read_b128 v[178:181], v164 offset:8864
	s_waitcnt vmcnt(0)
	v_add_u32_e32 v238, s26, v203
	ds_write_b128 v238, v[128:131]
	v_mfma_f32_32x32x16_bf16 v[64:79], v[182:185], v[108:111], v[64:79]
	ds_write_b128 v238, v[132:135] offset:128
	v_mfma_f32_32x32x16_bf16 v[80:95], v[190:193], v[96:99], v[80:95]
	ds_read_b128 v[182:185], v164 offset:192
	ds_read_b128 v[190:193], v164 offset:8896
	v_add_u32_e32 v239, s43, v204
	ds_write_b128 v239, v[136:139] offset:34816
	v_mfma_f32_32x32x16_bf16 v[64:79], v[186:189], v[96:99], v[64:79]
	ds_write_b128 v239, v[140:143] offset:44032
	v_mfma_f32_32x32x16_bf16 v[80:95], v[194:197], v[104:107], v[80:95]
	ds_read_b128 v[186:189], v164 offset:224
	ds_read_b128 v[194:197], v164 offset:8928
	s_cmp_gt_u32 s27, 61
	s_cbranch_scc1 .Lmy_a1_skipk
	s_cmp_eq_u32 s42, 60
	s_cselect_b64 vcc, -1, 0
	s_add_u32 s42, s6, s24
	v_cndmask_b32_e32 v242, v160, v201, vcc
	s_addc_u32 s43, s7, s25
	v_mov_b32_e32 v243, 0
	v_lshl_add_u64 v[240:241], s[42:43], 0, v[242:243]
	v_add_co_u32_e32 v240, vcc, 0x38b18000, v240
	s_nop 1
	v_addc_co_u32_e32 v241, vcc, 0, v241, vcc
	global_load_dwordx4 v[128:131], v[240:241], off
	global_load_dwordx4 v[132:135], v[240:241], off offset:128
; DI unsigned cvtpk(float lo, float hi) { f32x2 v = {lo, hi}; return __builtin_bit_cast(unsigned, __builtin_convertvector(v, bf16x2_t)); }
; #define B_FRAG(dst_, i_) do { if ((i_) < NQK) { dst_ = *(const bf16x8*)(sk + ((i_) & 1) * (32 * KSTR) + ((i_) >> 1) * 32); } \
;           else { dst_ = *(const bf16x8*)(sv + (((i_) - NQK) & 3) * (32 * VSTR) + (((i_) - NQK) >> 2) * 32); } } while (0)
; template <int NHQ, int NHKV>
; DI void attn_phase_l1(const u16* __restrict__ Q, const u16* __restrict__ K, const u16* __restrict__ Vt, u16* __restrict__ O, const float* __restrict__ qg, char* smem, const int wv) {
;     ...
;         for (int i = 0; i < NM; ++i) {
;           if (i < NQK) {
;             if (i & 1) s1 = __builtin_amdgcn_mfma_f32_32x32x16_bf16(ring[i % RING], qf[i >> 1], s1, 0, 0, 0);
;             else       s0 = __builtin_amdgcn_mfma_f32_32x32x16_bf16(ring[i % RING], qf[i >> 1], s0, 0, 0, 0);
;           } else {
;             o[(i - NQK) & 3] = __builtin_amdgcn_mfma_f32_32x32x16_bf16(ring[i % RING], pb[(i - NQK) >> 2], o[(i - NQK) & 3], 0, 0, 0);
;           }
;           if (i + RING < NM) B_FRAG(ring[i % RING], i + RING);
;           if (i >= NQK + 2) {
;             const int g = i - NQK - 2;
;             f32x2 v;
;             if (g < 8) { v[0] = __builtin_amdgcn_exp2f(s0[2 * g]); v[1] = __builtin_amdgcn_exp2f(s0[2 * g + 1]); }
;             else       { v[0] = __builtin_amdgcn_exp2f(s1[2 * (g - 8)]); v[1] = __builtin_amdgcn_exp2f(s1[2 * (g - 8) + 1]); }
;             ps2 += v; w_[g] = cvtpk(v[0], v[1]);
;           }
;           __builtin_amdgcn_sched_barrier(0);
;         }
; #pragma unroll
;         for (int g = 14; g < 16; ++g) { f32x2 v; v[0] = __builtin_amdgcn_exp2f(s1[2 * (g - 8)]); v[1] = __builtin_amdgcn_exp2f(s1[2 * (g - 8) + 1]); ps2 += v; w_[g] = cvtpk(v[0], v[1]); }
;     ...
;         if (j + 1 < NT) {
;           l += ps2[0] + ps2[1];
; #pragma unroll
;           for (int q = 0; q < 4; ++q) pb[q] = __builtin_bit_cast(bf16x8, u32x4{w_[4 * q], w_[4 * q + 1], w_[4 * q + 2], w_[4 * q + 3]});
;         }
.Lmy_a1_skipk:
	v_mfma_f32_32x32x16_bf16 v[64:79], v[214:217], v[104:107], v[64:79]
	v_lshl_add_u64 v[240:241], s[6:7], 0, v[174:175]
	v_add_co_u32_e32 v244, vcc, 0x29900000, v240
	s_nop 1
	v_addc_co_u32_e32 v245, vcc, 0, v241, vcc
	v_add_co_u32_e32 v240, vcc, 0x29982000, v240
	s_nop 1
	v_addc_co_u32_e32 v241, vcc, 0, v241, vcc
	global_load_dwordx4 v[136:139], v[244:245], off offset:256
	global_load_dwordx4 v[140:143], v[240:241], off offset:256
	s_waitcnt lgkmcnt(11)
	v_mfma_f32_32x32x16_bf16 v[80:95], v[220:223], v[116:119], v[80:95]
	ds_read_b128 v[214:217], v177 offset:34816
	ds_read_b128 v[220:223], v177 offset:39424
	s_waitcnt lgkmcnt(11)
	v_mfma_f32_32x32x16_bf16 v[64:79], v[224:227], v[116:119], v[64:79]
	v_mfma_f32_32x32x16_bf16 v[80:95], v[228:231], v[120:123], v[80:95]
	ds_read_b128 v[224:227], v177 offset:44032
	ds_read_b128 v[228:231], v177 offset:48640
	s_waitcnt lgkmcnt(9)
	v_mfma_f32_32x32x16_bf16 v[64:79], v[178:181], v[120:123], v[64:79]
	v_mfma_f32_32x32x16_bf16 v[80:95], v[182:185], v[112:115], v[80:95]
	ds_read_b128 v[178:181], v177 offset:34848
	ds_read_b128 v[182:185], v177 offset:39456
	s_waitcnt lgkmcnt(7)
	v_mfma_f32_32x32x16_bf16 v[64:79], v[190:193], v[112:115], v[64:79]
	v_mfma_f32_32x32x16_bf16 v[80:95], v[186:189], v[124:127], v[80:95]
	ds_read_b128 v[190:193], v177 offset:44064
	ds_read_b128 v[186:189], v177 offset:48672
	s_waitcnt lgkmcnt(7)
	v_mfma_f32_32x32x16_bf16 v[64:79], v[194:197], v[124:127], v[64:79]
	v_mfma_f32_32x32x16_bf16 v[48:63], v[214:217], v[144:147], v[48:63]
	ds_read_b128 v[194:197], v177 offset:34880
	s_waitcnt lgkmcnt(7)
	v_mfma_f32_32x32x16_bf16 v[32:47], v[220:223], v[144:147], v[32:47]
	ds_read_b128 v[214:217], v177 offset:39488
	s_waitcnt lgkmcnt(7)
	v_mfma_f32_32x32x16_bf16 v[16:31], v[224:227], v[144:147], v[16:31]
	s_nop 0
	v_exp_f32_e32 v80, v80
	v_exp_f32_e32 v81, v81
	ds_read_b128 v[220:223], v177 offset:44096
	v_mov_b32_e32 v198, v80
	v_mov_b32_e32 v199, v81
	v_cvt_pk_bf16_f32 v80, v80, v81
	s_waitcnt lgkmcnt(7)
	v_mfma_f32_32x32x16_bf16 v[0:15], v[228:231], v[144:147], v[0:15]
	v_exp_f32_e32 v82, v82
	v_exp_f32_e32 v83, v83
	ds_read_b128 v[224:227], v177 offset:48704
	v_cvt_pk_bf16_f32 v145, v82, v83
	v_add_f32_e32 v198, v82, v198
	v_add_f32_e32 v199, v83, v199
	s_waitcnt lgkmcnt(7)
	v_mfma_f32_32x32x16_bf16 v[48:63], v[178:181], v[148:151], v[48:63]
	v_exp_f32_e32 v82, v84
	v_exp_f32_e32 v83, v85
	ds_read_b128 v[228:231], v177 offset:34912
	v_add_f32_e32 v84, v82, v198
	v_add_f32_e32 v85, v83, v199
	v_cvt_pk_bf16_f32 v146, v82, v83
	s_waitcnt lgkmcnt(7)
	v_mfma_f32_32x32x16_bf16 v[32:47], v[182:185], v[148:151], v[32:47]
	v_exp_f32_e32 v82, v86
	v_exp_f32_e32 v83, v87
	ds_read_b128 v[178:181], v177 offset:39520
	v_add_f32_e32 v84, v82, v84
	v_add_f32_e32 v85, v83, v85
	v_cvt_pk_bf16_f32 v147, v82, v83
	s_waitcnt lgkmcnt(7)
	v_mfma_f32_32x32x16_bf16 v[16:31], v[190:193], v[148:151], v[16:31]
	v_exp_f32_e32 v82, v88
	v_exp_f32_e32 v83, v89
	ds_read_b128 v[182:185], v177 offset:44128
	v_add_f32_e32 v86, v82, v84
	v_add_f32_e32 v87, v83, v85
	v_cvt_pk_bf16_f32 v84, v82, v83
	s_waitcnt lgkmcnt(7)
	v_mfma_f32_32x32x16_bf16 v[0:15], v[186:189], v[148:151], v[0:15]
	v_exp_f32_e32 v82, v90
	v_exp_f32_e32 v83, v91
	ds_read_b128 v[190:193], v177 offset:48736
	v_cvt_pk_bf16_f32 v149, v82, v83
	v_add_f32_e32 v86, v82, v86
	v_add_f32_e32 v87, v83, v87
	s_waitcnt lgkmcnt(7)
	v_mfma_f32_32x32x16_bf16 v[48:63], v[194:197], v[152:155], v[48:63]
	v_exp_f32_e32 v82, v92
	v_exp_f32_e32 v83, v93
	s_nop 0
	v_cvt_pk_bf16_f32 v150, v82, v83
	v_add_f32_e32 v86, v82, v86
	v_add_f32_e32 v87, v83, v87
	s_waitcnt lgkmcnt(6)
	v_mfma_f32_32x32x16_bf16 v[32:47], v[214:217], v[152:155], v[32:47]
	v_exp_f32_e32 v82, v94
	v_exp_f32_e32 v83, v95
	s_nop 0
	v_cvt_pk_bf16_f32 v151, v82, v83
	v_add_f32_e32 v86, v82, v86
	v_add_f32_e32 v87, v83, v87
	v_add_f32_e32 v86, v86, v87
	v_add_f32_e32 v176, v176, v86
	s_waitcnt lgkmcnt(5)
	v_mfma_f32_32x32x16_bf16 v[16:31], v[220:223], v[152:155], v[16:31]
	s_waitcnt lgkmcnt(4)
	v_mfma_f32_32x32x16_bf16 v[0:15], v[224:227], v[152:155], v[0:15]
	s_waitcnt lgkmcnt(3)
	v_mfma_f32_32x32x16_bf16 v[48:63], v[228:231], v[156:159], v[48:63]
	s_waitcnt lgkmcnt(2)
	v_mfma_f32_32x32x16_bf16 v[32:47], v[178:181], v[156:159], v[32:47]
	s_waitcnt lgkmcnt(1)
	v_mfma_f32_32x32x16_bf16 v[16:31], v[182:185], v[156:159], v[16:31]
	s_waitcnt lgkmcnt(0)
	v_mfma_f32_32x32x16_bf16 v[0:15], v[190:193], v[156:159], v[0:15]
	s_waitcnt lgkmcnt(0)
	s_barrier
	s_add_u32 s24, s24, 0x8000
	s_addc_u32 s25, s25, 0
	s_cmp_eq_u32 s27, 62
	v_lshl_add_u64 v[174:175], v[174:175], 0, s[16:17]
	s_cbranch_scc1 .La_exit
	s_mov_b32 s42, s27
	s_branch .LBB0_1217
.La_exit:
	v_exp_f32_e32 v250, v64
	v_exp_f32_e32 v251, v65
	s_nop 0
	v_add_f32_e32 v254, 0, v250
	v_add_f32_e32 v255, 0, v251
	v_exp_f32_e32 v252, v66
	v_exp_f32_e32 v253, v67
	v_cvt_pk_bf16_f32 v88, v250, v251
	v_add_f32_e32 v254, v252, v254
	v_add_f32_e32 v255, v253, v255
	v_exp_f32_e32 v250, v68
	v_exp_f32_e32 v251, v69
	v_cvt_pk_bf16_f32 v153, v252, v253
	v_add_f32_e32 v254, v250, v254
	v_add_f32_e32 v255, v251, v255
	v_exp_f32_e32 v252, v70
	v_exp_f32_e32 v253, v71
	v_cvt_pk_bf16_f32 v154, v250, v251
	v_add_f32_e32 v254, v252, v254
	v_add_f32_e32 v255, v253, v255
	v_exp_f32_e32 v250, v72
	v_exp_f32_e32 v251, v73
	v_cvt_pk_bf16_f32 v155, v252, v253
	v_add_f32_e32 v254, v250, v254
	v_add_f32_e32 v255, v251, v255
	v_exp_f32_e32 v252, v74
	v_exp_f32_e32 v253, v75
	v_cvt_pk_bf16_f32 v92, v250, v251
	v_add_f32_e32 v254, v252, v254
	v_add_f32_e32 v255, v253, v255
	v_exp_f32_e32 v250, v76
	v_exp_f32_e32 v251, v77
	v_cvt_pk_bf16_f32 v157, v252, v253
	v_add_f32_e32 v254, v250, v254
	v_add_f32_e32 v255, v251, v255
	v_exp_f32_e32 v252, v78
	v_exp_f32_e32 v253, v79
	v_cvt_pk_bf16_f32 v158, v250, v251
	v_add_f32_e32 v254, v252, v254
	v_add_f32_e32 v255, v253, v255
	v_cvt_pk_bf16_f32 v159, v252, v253
	v_add_f32_e32 v254, v254, v255
	v_add_f32_e32 v176, v176, v254
	s_branch .LBB0_1215
